# adds: MIN/UP weights pre-transposed in the same wave-contiguous column order as QKV; MIN/UP epilogue exchanges row pairs through DPP so every store writes 8 full 128-byte lines instead of 16 half line
# baseline (speedup 1.0000x reference)
; __device__ __forceinline__ unsigned cvt_pk_bf16(float lo, float hi) { unsigned r; asm volatile("v_cvt_pk_bf16_f32 %0, %1, %2" : "=v"(r) : "v"(lo), "v"(hi)); return r; }
;     __device__ __forceinline__ void operator()(const f32x4 (&acc)[2][2][4][2], const Unit& u, int wr, int wc, int fr, int fq) const {
;     ...
; #pragma unroll
;         for (int ai = 0; ai < 2; ++ai)
; #pragma unroll
;             for (int m = 0; m < 4; ++m) {
;                 const int r = row0 + ai * HALF + m * 16;
;                 const float rs = __builtin_amdgcn_rsqf((float)ss[r] * (1.0f / 1048576.0f) * (1.0f / 1024.0f) + EPS);
;                 bf16_t* rowp = O + (size_t)r * ldc + colt + wc * 32 + 8 * fq;
; #pragma unroll
;                 for (int bj = 0; bj < 2; ++bj) { f32x4 v0 = acc[ai][bj][m][0] * rs, v1 = acc[ai][bj][m][1] * rs;
;                     if (mode == 2) {
; #pragma unroll
;                         for (int e = 0; e < 4; ++e) { float a = fmaxf(v0[e], 0.f), b = fmaxf(v1[e], 0.f); v0[e] = a * a; v1[e] = b * b; } }
;                     if (mode == 1 && colt >= 2048) {
; #pragma unroll
;                         for (int e = 0; e < 4; ++e) { v0[e] = __builtin_amdgcn_rcpf(1.0f + __builtin_amdgcn_exp2f(-1.4426950408889634f * v0[e])); v1[e] = __builtin_amdgcn_rcpf(1.0f + __builtin_amdgcn_exp2f(-1.4426950408889634f * v1[e])); } }
;                     u32x4 w; w.x = cvt_pk_bf16(v0[0], v0[1]); w.y = cvt_pk_bf16(v0[2], v0[3]); w.z = cvt_pk_bf16(v1[0], v1[1]); w.w = cvt_pk_bf16(v1[2], v1[3]);
.LBB0_364:
	v_mad_i64_i32 v[84:85], s[42:43], s54, v160, 0
	s_ashr_i32 s77, s76, 31
	v_lshl_add_u64 v[84:85], v[84:85], 1, s[28:29]
	v_lshl_add_u64 v[84:85], s[76:77], 1, v[84:85]
	s_lshl_b32 s34, s83, 2
	v_lshl_add_u64 v[84:85], v[84:85], 0, s[34:35]
	v_lshlrev_b32_e32 v112, 1, v154
	v_lshl_add_u64 v[84:85], v[84:85], 0, v[112:113]
	v_mov_b32_e32 v210, s54
	v_mov_b32_e32 v211, 0
	v_lshlrev_b32_e32 v210, 5, v210
	v_mov_b32_e32 v213, 0
	v_mul_u32_u24_e32 v212, 5, v210
	v_lshl_add_u64 v[208:209], v[84:85], 0, v[210:211]
	s_mov_b32 vcc_lo, 0xff00ff00
	s_mov_b32 vcc_hi, 0xff00ff00
	v_mov_b32_e32 v216, s54
	v_lshlrev_b32_e32 v216, 4, v216
	v_sub_u32_e32 v214, 64, v216
	v_cndmask_b32_e32 v214, 0, v214, vcc
	v_cndmask_b32_e64 v215, 0, -1, vcc
	v_cndmask_b32_e64 v216, v216, 64, vcc
	v_mov_b32_e32 v217, 0
	v_cvt_pk_bf16_f32 v90, v90, v91
	v_cvt_pk_bf16_f32 v91, v86, v87
	v_cvt_pk_bf16_f32 v92, v92, v93
	v_mov_b32_e32 v83, v82
	v_cvt_pk_bf16_f32 v93, v88, v89
	v_mov_b32_e32 v218, v90
	v_mov_b32_e32 v219, v91
	v_mov_b32_e32 v220, v92
	v_mov_b32_e32 v221, v93
	v_mov_b32_e32 v88, v82
	v_mov_b32_e32 v89, v82
	v_cndmask_b32_e64 v92, 0, 1, s[50:51]
	v_pk_mul_f32 v[86:87], v[136:137], v[88:89]
	v_pk_mul_f32 v[90:91], v[134:135], v[82:83]
	v_pk_mul_f32 v[88:89], v[132:133], v[88:89]
	v_cmp_ne_u32_e64 s[42:43], 1, v92
	s_andn2_b64 vcc, exec, s[50:51]
	v_pk_mul_f32 v[82:83], v[130:131], v[82:83]
	s_cbranch_vccnz .LBB0_366
	v_max_f32_e32 v90, 0, v90
	v_max_f32_e32 v82, 0, v82
	v_max_f32_e32 v91, 0, v91
	v_max_f32_e32 v83, 0, v83
	v_max_f32_e32 v86, 0, v86
	v_max_f32_e32 v88, 0, v88
	v_max_f32_e32 v87, 0, v87
	v_max_f32_e32 v89, 0, v89
	v_pk_mul_f32 v[90:91], v[90:91], v[90:91]
	v_pk_mul_f32 v[86:87], v[86:87], v[86:87]
	v_pk_mul_f32 v[82:83], v[82:83], v[82:83]
	v_pk_mul_f32 v[88:89], v[88:89], v[88:89]

; __device__ __forceinline__ unsigned cvt_pk_bf16(float lo, float hi) { unsigned r; asm volatile("v_cvt_pk_bf16_f32 %0, %1, %2" : "=v"(r) : "v"(lo), "v"(hi)); return r; }
;     __device__ __forceinline__ void operator()(const f32x4 (&acc)[2][2][4][2], const Unit& u, int wr, int wc, int fr, int fq) const {
;     ...
; #pragma unroll
;         for (int ai = 0; ai < 2; ++ai)
; #pragma unroll
;             for (int m = 0; m < 4; ++m) {
;                 const int r = row0 + ai * HALF + m * 16;
;                 const float rs = __builtin_amdgcn_rsqf((float)ss[r] * (1.0f / 1048576.0f) * (1.0f / 1024.0f) + EPS);
;                 bf16_t* rowp = O + (size_t)r * ldc + colt + wc * 32 + 8 * fq;
; #pragma unroll
;                 for (int bj = 0; bj < 2; ++bj) { f32x4 v0 = acc[ai][bj][m][0] * rs, v1 = acc[ai][bj][m][1] * rs;
;                     if (mode == 2) {
; #pragma unroll
;                         for (int e = 0; e < 4; ++e) { float a = fmaxf(v0[e], 0.f), b = fmaxf(v1[e], 0.f); v0[e] = a * a; v1[e] = b * b; } }
;                     if (mode == 1 && colt >= 2048) {
; #pragma unroll
;                         for (int e = 0; e < 4; ++e) { v0[e] = __builtin_amdgcn_rcpf(1.0f + __builtin_amdgcn_exp2f(-1.4426950408889634f * v0[e])); v1[e] = __builtin_amdgcn_rcpf(1.0f + __builtin_amdgcn_exp2f(-1.4426950408889634f * v1[e])); } }
;                     u32x4 w; w.x = cvt_pk_bf16(v0[0], v0[1]); w.y = cvt_pk_bf16(v0[2], v0[3]); w.z = cvt_pk_bf16(v1[0], v1[1]); w.w = cvt_pk_bf16(v1[2], v1[3]);
;                     *(u32x4*)(rowp + bj * HALF) = w; }
.LBB0_368:
	v_cvt_pk_bf16_f32 v90, v90, v91
	v_cvt_pk_bf16_f32 v91, v86, v87
	v_cvt_pk_bf16_f32 v92, v82, v83
	v_cvt_pk_bf16_f32 v93, v88, v89
	s_mov_b32 vcc_lo, 0xff00ff00
	s_mov_b32 vcc_hi, 0xff00ff00
	v_mov_b32_dpp v222, v218 row_ror:8 row_mask:0xf bank_mask:0xf
	v_mov_b32_dpp v223, v219 row_ror:8 row_mask:0xf bank_mask:0xf
	v_mov_b32_dpp v224, v220 row_ror:8 row_mask:0xf bank_mask:0xf
	v_mov_b32_dpp v225, v221 row_ror:8 row_mask:0xf bank_mask:0xf
	v_mov_b32_dpp v242, v90 row_ror:8 row_mask:0xf bank_mask:0xf
	v_mov_b32_dpp v243, v91 row_ror:8 row_mask:0xf bank_mask:0xf
	v_mov_b32_dpp v244, v92 row_ror:8 row_mask:0xf bank_mask:0xf
	v_mov_b32_dpp v245, v93 row_ror:8 row_mask:0xf bank_mask:0xf
	v_lshl_add_u64 v[246:247], v[84:85], 0, v[214:215]
	v_lshl_add_u64 v[248:249], v[84:85], 0, v[216:217]
	v_cndmask_b32_e32 v242, v218, v242, vcc
	v_cndmask_b32_e32 v243, v219, v243, vcc
	v_cndmask_b32_e32 v244, v220, v244, vcc
	v_cndmask_b32_e32 v245, v221, v245, vcc
	v_cndmask_b32_e32 v222, v222, v90, vcc
	v_cndmask_b32_e32 v223, v223, v91, vcc
	v_cndmask_b32_e32 v224, v224, v92, vcc
	v_cndmask_b32_e32 v225, v225, v93, vcc
	global_store_dwordx4 v[246:247], v[242:245], off
	global_store_dwordx4 v[248:249], v[222:225], off
	s_and_b64 vcc, exec, s[42:43]
	s_nop 1
	v_cvt_f32_u32_e32 v83, v195
	v_cvt_f32_u32_e32 v82, v194
	v_fmamk_f32 v82, v83, 0x4f800000, v82
	v_fmamk_f32 v82, v82, 0x30800000, v229
	v_rsq_f32_e32 v82, v82
	s_nop 0
	v_pk_mul_f32 v[86:87], v[128:129], v[82:83] op_sel_hi:[1,0]
	v_pk_mul_f32 v[90:91], v[126:127], v[82:83] op_sel_hi:[1,0]
	v_pk_mul_f32 v[88:89], v[124:125], v[82:83] op_sel_hi:[1,0]
	v_pk_mul_f32 v[92:93], v[122:123], v[82:83] op_sel_hi:[1,0]
	s_cbranch_vccnz .LBB0_370
	v_max_f32_e32 v84, 0, v90
	v_max_f32_e32 v92, 0, v92
	v_max_f32_e32 v85, 0, v91
	v_max_f32_e32 v93, 0, v93
	v_max_f32_e32 v86, 0, v86
	v_max_f32_e32 v88, 0, v88
	v_max_f32_e32 v87, 0, v87
	v_max_f32_e32 v89, 0, v89
	v_pk_mul_f32 v[90:91], v[84:85], v[84:85]
	v_pk_mul_f32 v[86:87], v[86:87], v[86:87]
	v_pk_mul_f32 v[92:93], v[92:93], v[92:93]
	v_pk_mul_f32 v[88:89], v[88:89], v[88:89]

; __device__ __forceinline__ unsigned cvt_pk_bf16(float lo, float hi) { unsigned r; asm volatile("v_cvt_pk_bf16_f32 %0, %1, %2" : "=v"(r) : "v"(lo), "v"(hi)); return r; }
;     __device__ __forceinline__ void operator()(const f32x4 (&acc)[2][2][4][2], const Unit& u, int wr, int wc, int fr, int fq) const {
;     ...
; #pragma unroll
;         for (int ai = 0; ai < 2; ++ai)
; #pragma unroll
;             for (int m = 0; m < 4; ++m) {
;                 const int r = row0 + ai * HALF + m * 16;
;                 const float rs = __builtin_amdgcn_rsqf((float)ss[r] * (1.0f / 1048576.0f) * (1.0f / 1024.0f) + EPS);
;                 bf16_t* rowp = O + (size_t)r * ldc + colt + wc * 32 + 8 * fq;
; #pragma unroll
;                 for (int bj = 0; bj < 2; ++bj) { f32x4 v0 = acc[ai][bj][m][0] * rs, v1 = acc[ai][bj][m][1] * rs;
;                     if (mode == 2) {
; #pragma unroll
;                         for (int e = 0; e < 4; ++e) { float a = fmaxf(v0[e], 0.f), b = fmaxf(v1[e], 0.f); v0[e] = a * a; v1[e] = b * b; } }
;                     if (mode == 1 && colt >= 2048) {
; #pragma unroll
;                         for (int e = 0; e < 4; ++e) { v0[e] = __builtin_amdgcn_rcpf(1.0f + __builtin_amdgcn_exp2f(-1.4426950408889634f * v0[e])); v1[e] = __builtin_amdgcn_rcpf(1.0f + __builtin_amdgcn_exp2f(-1.4426950408889634f * v1[e])); } }
;                     u32x4 w; w.x = cvt_pk_bf16(v0[0], v0[1]); w.y = cvt_pk_bf16(v0[2], v0[3]); w.z = cvt_pk_bf16(v1[0], v1[1]); w.w = cvt_pk_bf16(v1[2], v1[3]);
;                     *(u32x4*)(rowp + bj * HALF) = w; }
.LBB0_372:
	v_mov_b32_e32 v83, v82
	v_cvt_pk_bf16_f32 v90, v90, v91
	v_cvt_pk_bf16_f32 v91, v86, v87
	v_cvt_pk_bf16_f32 v92, v92, v93
	v_cvt_pk_bf16_f32 v93, v88, v89
	v_mov_b32_e32 v88, v82
	v_mov_b32_e32 v89, v82
	v_mov_b32_e32 v218, v90
	v_mov_b32_e32 v219, v91
	v_mov_b32_e32 v220, v92
	v_mov_b32_e32 v221, v93
	v_pk_mul_f32 v[86:87], v[120:121], v[88:89]
	v_pk_mul_f32 v[88:89], v[116:117], v[88:89]
	v_pk_mul_f32 v[90:91], v[118:119], v[82:83]
	s_and_b64 vcc, exec, s[42:43]
	v_pk_mul_f32 v[82:83], v[114:115], v[82:83]
	s_cbranch_vccnz .LBB0_374
	v_max_f32_e32 v90, 0, v90
	v_max_f32_e32 v82, 0, v82
	v_max_f32_e32 v91, 0, v91
	v_max_f32_e32 v83, 0, v83
	v_max_f32_e32 v86, 0, v86
	v_max_f32_e32 v88, 0, v88
	v_max_f32_e32 v87, 0, v87
	v_max_f32_e32 v89, 0, v89
	v_pk_mul_f32 v[90:91], v[90:91], v[90:91]
	v_pk_mul_f32 v[86:87], v[86:87], v[86:87]
	v_pk_mul_f32 v[82:83], v[82:83], v[82:83]
	v_pk_mul_f32 v[88:89], v[88:89], v[88:89]

; __device__ __forceinline__ unsigned cvt_pk_bf16(float lo, float hi) { unsigned r; asm volatile("v_cvt_pk_bf16_f32 %0, %1, %2" : "=v"(r) : "v"(lo), "v"(hi)); return r; }
;     __device__ __forceinline__ void operator()(const f32x4 (&acc)[2][2][4][2], const Unit& u, int wr, int wc, int fr, int fq) const {
;     ...
; #pragma unroll
;         for (int ai = 0; ai < 2; ++ai)
; #pragma unroll
;             for (int m = 0; m < 4; ++m) {
;                 const int r = row0 + ai * HALF + m * 16;
;                 const float rs = __builtin_amdgcn_rsqf((float)ss[r] * (1.0f / 1048576.0f) * (1.0f / 1024.0f) + EPS);
;                 bf16_t* rowp = O + (size_t)r * ldc + colt + wc * 32 + 8 * fq;
; #pragma unroll
;                 for (int bj = 0; bj < 2; ++bj) { f32x4 v0 = acc[ai][bj][m][0] * rs, v1 = acc[ai][bj][m][1] * rs;
;                     if (mode == 2) {
; #pragma unroll
;                         for (int e = 0; e < 4; ++e) { float a = fmaxf(v0[e], 0.f), b = fmaxf(v1[e], 0.f); v0[e] = a * a; v1[e] = b * b; } }
;                     if (mode == 1 && colt >= 2048) {
; #pragma unroll
;                         for (int e = 0; e < 4; ++e) { v0[e] = __builtin_amdgcn_rcpf(1.0f + __builtin_amdgcn_exp2f(-1.4426950408889634f * v0[e])); v1[e] = __builtin_amdgcn_rcpf(1.0f + __builtin_amdgcn_exp2f(-1.4426950408889634f * v1[e])); } }
;                     u32x4 w; w.x = cvt_pk_bf16(v0[0], v0[1]); w.y = cvt_pk_bf16(v0[2], v0[3]); w.z = cvt_pk_bf16(v1[0], v1[1]); w.w = cvt_pk_bf16(v1[2], v1[3]);
;                     *(u32x4*)(rowp + bj * HALF) = w; }
.LBB0_376:
	v_cvt_pk_bf16_f32 v90, v90, v91
	v_cvt_pk_bf16_f32 v91, v86, v87
	v_cvt_pk_bf16_f32 v92, v82, v83
	v_cvt_pk_bf16_f32 v93, v88, v89
	s_mov_b32 vcc_lo, 0xff00ff00
	s_mov_b32 vcc_hi, 0xff00ff00
	v_mov_b32_dpp v222, v218 row_ror:8 row_mask:0xf bank_mask:0xf
	v_mov_b32_dpp v223, v219 row_ror:8 row_mask:0xf bank_mask:0xf
	v_mov_b32_dpp v224, v220 row_ror:8 row_mask:0xf bank_mask:0xf
	v_mov_b32_dpp v225, v221 row_ror:8 row_mask:0xf bank_mask:0xf
	v_mov_b32_dpp v242, v90 row_ror:8 row_mask:0xf bank_mask:0xf
	v_mov_b32_dpp v243, v91 row_ror:8 row_mask:0xf bank_mask:0xf
	v_mov_b32_dpp v244, v92 row_ror:8 row_mask:0xf bank_mask:0xf
	v_mov_b32_dpp v245, v93 row_ror:8 row_mask:0xf bank_mask:0xf
	v_lshl_add_u64 v[246:247], v[208:209], 0, v[214:215]
	v_lshl_add_u64 v[248:249], v[208:209], 0, v[216:217]
	v_cndmask_b32_e32 v242, v218, v242, vcc
	v_cndmask_b32_e32 v243, v219, v243, vcc
	v_cndmask_b32_e32 v244, v220, v244, vcc
	v_cndmask_b32_e32 v245, v221, v245, vcc
	v_cndmask_b32_e32 v222, v222, v90, vcc
	v_cndmask_b32_e32 v223, v223, v91, vcc
	v_cndmask_b32_e32 v224, v224, v92, vcc
	v_cndmask_b32_e32 v225, v225, v93, vcc
	global_store_dwordx4 v[246:247], v[242:245], off
	global_store_dwordx4 v[248:249], v[222:225], off
	v_lshl_add_u64 v[208:209], v[208:209], 0, v[210:211]
	s_and_b64 vcc, exec, s[42:43]
	s_nop 1
	v_cvt_f32_u32_e32 v83, v197
	v_cvt_f32_u32_e32 v82, v196
	v_fmamk_f32 v82, v83, 0x4f800000, v82
	v_fmamk_f32 v82, v82, 0x30800000, v229
	v_rsq_f32_e32 v82, v82
	s_nop 0
	v_pk_mul_f32 v[86:87], v[110:111], v[82:83] op_sel_hi:[1,0]
	v_pk_mul_f32 v[90:91], v[108:109], v[82:83] op_sel_hi:[1,0]
	v_pk_mul_f32 v[88:89], v[106:107], v[82:83] op_sel_hi:[1,0]
	v_pk_mul_f32 v[92:93], v[104:105], v[82:83] op_sel_hi:[1,0]
	s_cbranch_vccnz .LBB0_378
	v_max_f32_e32 v84, 0, v90
	v_max_f32_e32 v92, 0, v92
	v_max_f32_e32 v85, 0, v91
	v_max_f32_e32 v93, 0, v93
	v_max_f32_e32 v86, 0, v86
	v_max_f32_e32 v88, 0, v88
	v_max_f32_e32 v87, 0, v87
	v_max_f32_e32 v89, 0, v89
	v_pk_mul_f32 v[90:91], v[84:85], v[84:85]
	v_pk_mul_f32 v[86:87], v[86:87], v[86:87]
	v_pk_mul_f32 v[92:93], v[92:93], v[92:93]
	v_pk_mul_f32 v[88:89], v[88:89], v[88:89]

; __device__ __forceinline__ unsigned cvt_pk_bf16(float lo, float hi) { unsigned r; asm volatile("v_cvt_pk_bf16_f32 %0, %1, %2" : "=v"(r) : "v"(lo), "v"(hi)); return r; }
;     __device__ __forceinline__ void operator()(const f32x4 (&acc)[2][2][4][2], const Unit& u, int wr, int wc, int fr, int fq) const {
;     ...
; #pragma unroll
;         for (int ai = 0; ai < 2; ++ai)
; #pragma unroll
;             for (int m = 0; m < 4; ++m) {
;                 const int r = row0 + ai * HALF + m * 16;
;                 const float rs = __builtin_amdgcn_rsqf((float)ss[r] * (1.0f / 1048576.0f) * (1.0f / 1024.0f) + EPS);
;                 bf16_t* rowp = O + (size_t)r * ldc + colt + wc * 32 + 8 * fq;
; #pragma unroll
;                 for (int bj = 0; bj < 2; ++bj) { f32x4 v0 = acc[ai][bj][m][0] * rs, v1 = acc[ai][bj][m][1] * rs;
;                     if (mode == 2) {
; #pragma unroll
;                         for (int e = 0; e < 4; ++e) { float a = fmaxf(v0[e], 0.f), b = fmaxf(v1[e], 0.f); v0[e] = a * a; v1[e] = b * b; } }
;                     if (mode == 1 && colt >= 2048) {
; #pragma unroll
;                         for (int e = 0; e < 4; ++e) { v0[e] = __builtin_amdgcn_rcpf(1.0f + __builtin_amdgcn_exp2f(-1.4426950408889634f * v0[e])); v1[e] = __builtin_amdgcn_rcpf(1.0f + __builtin_amdgcn_exp2f(-1.4426950408889634f * v1[e])); } }
;                     u32x4 w; w.x = cvt_pk_bf16(v0[0], v0[1]); w.y = cvt_pk_bf16(v0[2], v0[3]); w.z = cvt_pk_bf16(v1[0], v1[1]); w.w = cvt_pk_bf16(v1[2], v1[3]);
;                     *(u32x4*)(rowp + bj * HALF) = w; }
.LBB0_380:
	v_mov_b32_e32 v83, v82
	v_cvt_pk_bf16_f32 v90, v90, v91
	v_cvt_pk_bf16_f32 v91, v86, v87
	v_cvt_pk_bf16_f32 v92, v92, v93
	v_cvt_pk_bf16_f32 v93, v88, v89
	v_mov_b32_e32 v88, v82
	v_mov_b32_e32 v89, v82
	v_mov_b32_e32 v218, v90
	v_mov_b32_e32 v219, v91
	v_mov_b32_e32 v220, v92
	v_mov_b32_e32 v221, v93
	v_pk_mul_f32 v[86:87], v[102:103], v[88:89]
	v_pk_mul_f32 v[88:89], v[98:99], v[88:89]
	v_pk_mul_f32 v[90:91], v[100:101], v[82:83]
	s_and_b64 vcc, exec, s[42:43]
	v_pk_mul_f32 v[82:83], v[96:97], v[82:83]
	s_cbranch_vccnz .LBB0_382
	v_max_f32_e32 v90, 0, v90
	v_max_f32_e32 v82, 0, v82
	v_max_f32_e32 v91, 0, v91
	v_max_f32_e32 v83, 0, v83
	v_max_f32_e32 v86, 0, v86
	v_max_f32_e32 v88, 0, v88
	v_max_f32_e32 v87, 0, v87
	v_max_f32_e32 v89, 0, v89
	v_pk_mul_f32 v[90:91], v[90:91], v[90:91]
	v_pk_mul_f32 v[86:87], v[86:87], v[86:87]
	v_pk_mul_f32 v[82:83], v[82:83], v[82:83]
	v_pk_mul_f32 v[88:89], v[88:89], v[88:89]

; __device__ __forceinline__ unsigned cvt_pk_bf16(float lo, float hi) { unsigned r; asm volatile("v_cvt_pk_bf16_f32 %0, %1, %2" : "=v"(r) : "v"(lo), "v"(hi)); return r; }
;     __device__ __forceinline__ void operator()(const f32x4 (&acc)[2][2][4][2], const Unit& u, int wr, int wc, int fr, int fq) const {
;     ...
; #pragma unroll
;         for (int ai = 0; ai < 2; ++ai)
; #pragma unroll
;             for (int m = 0; m < 4; ++m) {
;                 const int r = row0 + ai * HALF + m * 16;
;                 const float rs = __builtin_amdgcn_rsqf((float)ss[r] * (1.0f / 1048576.0f) * (1.0f / 1024.0f) + EPS);
;                 bf16_t* rowp = O + (size_t)r * ldc + colt + wc * 32 + 8 * fq;
; #pragma unroll
;                 for (int bj = 0; bj < 2; ++bj) { f32x4 v0 = acc[ai][bj][m][0] * rs, v1 = acc[ai][bj][m][1] * rs;
;                     if (mode == 2) {
; #pragma unroll
;                         for (int e = 0; e < 4; ++e) { float a = fmaxf(v0[e], 0.f), b = fmaxf(v1[e], 0.f); v0[e] = a * a; v1[e] = b * b; } }
;                     if (mode == 1 && colt >= 2048) {
; #pragma unroll
;                         for (int e = 0; e < 4; ++e) { v0[e] = __builtin_amdgcn_rcpf(1.0f + __builtin_amdgcn_exp2f(-1.4426950408889634f * v0[e])); v1[e] = __builtin_amdgcn_rcpf(1.0f + __builtin_amdgcn_exp2f(-1.4426950408889634f * v1[e])); } }
;                     u32x4 w; w.x = cvt_pk_bf16(v0[0], v0[1]); w.y = cvt_pk_bf16(v0[2], v0[3]); w.z = cvt_pk_bf16(v1[0], v1[1]); w.w = cvt_pk_bf16(v1[2], v1[3]);
;                     *(u32x4*)(rowp + bj * HALF) = w; }
.LBB0_384:
	v_cvt_pk_bf16_f32 v90, v90, v91
	v_cvt_pk_bf16_f32 v91, v86, v87
	v_cvt_pk_bf16_f32 v92, v82, v83
	v_cvt_pk_bf16_f32 v93, v88, v89
	s_mov_b32 vcc_lo, 0xff00ff00
	s_mov_b32 vcc_hi, 0xff00ff00
	v_mov_b32_dpp v222, v218 row_ror:8 row_mask:0xf bank_mask:0xf
	v_mov_b32_dpp v223, v219 row_ror:8 row_mask:0xf bank_mask:0xf
	v_mov_b32_dpp v224, v220 row_ror:8 row_mask:0xf bank_mask:0xf
	v_mov_b32_dpp v225, v221 row_ror:8 row_mask:0xf bank_mask:0xf
	v_mov_b32_dpp v242, v90 row_ror:8 row_mask:0xf bank_mask:0xf
	v_mov_b32_dpp v243, v91 row_ror:8 row_mask:0xf bank_mask:0xf
	v_mov_b32_dpp v244, v92 row_ror:8 row_mask:0xf bank_mask:0xf
	v_mov_b32_dpp v245, v93 row_ror:8 row_mask:0xf bank_mask:0xf
	v_lshl_add_u64 v[246:247], v[208:209], 0, v[214:215]
	v_lshl_add_u64 v[248:249], v[208:209], 0, v[216:217]
	v_cndmask_b32_e32 v242, v218, v242, vcc
	v_cndmask_b32_e32 v243, v219, v243, vcc
	v_cndmask_b32_e32 v244, v220, v244, vcc
	v_cndmask_b32_e32 v245, v221, v245, vcc
	v_cndmask_b32_e32 v222, v222, v90, vcc
	v_cndmask_b32_e32 v223, v223, v91, vcc
	v_cndmask_b32_e32 v224, v224, v92, vcc
	v_cndmask_b32_e32 v225, v225, v93, vcc
	global_store_dwordx4 v[246:247], v[242:245], off
	global_store_dwordx4 v[248:249], v[222:225], off
	v_lshl_add_u64 v[208:209], v[208:209], 0, v[210:211]
	s_and_b64 vcc, exec, s[42:43]
	s_nop 1
	v_cvt_f32_u32_e32 v83, v199
	v_cvt_f32_u32_e32 v82, v198
	v_fmamk_f32 v82, v83, 0x4f800000, v82
	v_fmamk_f32 v82, v82, 0x30800000, v229
	v_rsq_f32_e32 v82, v82
	s_nop 0
	v_pk_mul_f32 v[86:87], v[78:79], v[82:83] op_sel_hi:[1,0]
	v_pk_mul_f32 v[90:91], v[76:77], v[82:83] op_sel_hi:[1,0]
	v_pk_mul_f32 v[88:89], v[74:75], v[82:83] op_sel_hi:[1,0]
	v_pk_mul_f32 v[92:93], v[72:73], v[82:83] op_sel_hi:[1,0]
	s_cbranch_vccnz .LBB0_386
	v_max_f32_e32 v84, 0, v90
	v_max_f32_e32 v92, 0, v92
	v_max_f32_e32 v85, 0, v91
	v_max_f32_e32 v93, 0, v93
	v_max_f32_e32 v86, 0, v86
	v_max_f32_e32 v88, 0, v88
	v_max_f32_e32 v87, 0, v87
	v_max_f32_e32 v89, 0, v89
	v_pk_mul_f32 v[90:91], v[84:85], v[84:85]
	v_pk_mul_f32 v[86:87], v[86:87], v[86:87]
	v_pk_mul_f32 v[92:93], v[92:93], v[92:93]
	v_pk_mul_f32 v[88:89], v[88:89], v[88:89]

; __device__ __forceinline__ unsigned cvt_pk_bf16(float lo, float hi) { unsigned r; asm volatile("v_cvt_pk_bf16_f32 %0, %1, %2" : "=v"(r) : "v"(lo), "v"(hi)); return r; }
;     __device__ __forceinline__ void operator()(const f32x4 (&acc)[2][2][4][2], const Unit& u, int wr, int wc, int fr, int fq) const {
;     ...
; #pragma unroll
;         for (int ai = 0; ai < 2; ++ai)
; #pragma unroll
;             for (int m = 0; m < 4; ++m) {
;                 const int r = row0 + ai * HALF + m * 16;
;                 const float rs = __builtin_amdgcn_rsqf((float)ss[r] * (1.0f / 1048576.0f) * (1.0f / 1024.0f) + EPS);
;                 bf16_t* rowp = O + (size_t)r * ldc + colt + wc * 32 + 8 * fq;
; #pragma unroll
;                 for (int bj = 0; bj < 2; ++bj) { f32x4 v0 = acc[ai][bj][m][0] * rs, v1 = acc[ai][bj][m][1] * rs;
;                     if (mode == 2) {
; #pragma unroll
;                         for (int e = 0; e < 4; ++e) { float a = fmaxf(v0[e], 0.f), b = fmaxf(v1[e], 0.f); v0[e] = a * a; v1[e] = b * b; } }
;                     if (mode == 1 && colt >= 2048) {
; #pragma unroll
;                         for (int e = 0; e < 4; ++e) { v0[e] = __builtin_amdgcn_rcpf(1.0f + __builtin_amdgcn_exp2f(-1.4426950408889634f * v0[e])); v1[e] = __builtin_amdgcn_rcpf(1.0f + __builtin_amdgcn_exp2f(-1.4426950408889634f * v1[e])); } }
;                     u32x4 w; w.x = cvt_pk_bf16(v0[0], v0[1]); w.y = cvt_pk_bf16(v0[2], v0[3]); w.z = cvt_pk_bf16(v1[0], v1[1]); w.w = cvt_pk_bf16(v1[2], v1[3]);
;                     *(u32x4*)(rowp + bj * HALF) = w; }
.LBB0_388:
	v_mov_b32_e32 v83, v82
	v_cvt_pk_bf16_f32 v90, v90, v91
	v_cvt_pk_bf16_f32 v91, v86, v87
	v_cvt_pk_bf16_f32 v92, v92, v93
	v_cvt_pk_bf16_f32 v93, v88, v89
	v_mov_b32_e32 v88, v82
	v_mov_b32_e32 v89, v82
	v_mov_b32_e32 v218, v90
	v_mov_b32_e32 v219, v91
	v_mov_b32_e32 v220, v92
	v_mov_b32_e32 v221, v93
	v_pk_mul_f32 v[86:87], v[70:71], v[88:89]
	v_pk_mul_f32 v[88:89], v[66:67], v[88:89]
	v_pk_mul_f32 v[90:91], v[68:69], v[82:83]
	s_and_b64 vcc, exec, s[42:43]
	v_pk_mul_f32 v[82:83], v[64:65], v[82:83]
	s_cbranch_vccnz .LBB0_390
	v_max_f32_e32 v90, 0, v90
	v_max_f32_e32 v82, 0, v82
	v_max_f32_e32 v91, 0, v91
	v_max_f32_e32 v83, 0, v83
	v_max_f32_e32 v86, 0, v86
	v_max_f32_e32 v88, 0, v88
	v_max_f32_e32 v87, 0, v87
	v_max_f32_e32 v89, 0, v89
	v_pk_mul_f32 v[90:91], v[90:91], v[90:91]
	v_pk_mul_f32 v[86:87], v[86:87], v[86:87]
	v_pk_mul_f32 v[82:83], v[82:83], v[82:83]
	v_pk_mul_f32 v[88:89], v[88:89], v[88:89]

; __device__ __forceinline__ unsigned cvt_pk_bf16(float lo, float hi) { unsigned r; asm volatile("v_cvt_pk_bf16_f32 %0, %1, %2" : "=v"(r) : "v"(lo), "v"(hi)); return r; }
;     __device__ __forceinline__ void operator()(const f32x4 (&acc)[2][2][4][2], const Unit& u, int wr, int wc, int fr, int fq) const {
;     ...
; #pragma unroll
;         for (int ai = 0; ai < 2; ++ai)
; #pragma unroll
;             for (int m = 0; m < 4; ++m) {
;                 const int r = row0 + ai * HALF + m * 16;
;                 const float rs = __builtin_amdgcn_rsqf((float)ss[r] * (1.0f / 1048576.0f) * (1.0f / 1024.0f) + EPS);
;                 bf16_t* rowp = O + (size_t)r * ldc + colt + wc * 32 + 8 * fq;
; #pragma unroll
;                 for (int bj = 0; bj < 2; ++bj) { f32x4 v0 = acc[ai][bj][m][0] * rs, v1 = acc[ai][bj][m][1] * rs;
;                     if (mode == 2) {
; #pragma unroll
;                         for (int e = 0; e < 4; ++e) { float a = fmaxf(v0[e], 0.f), b = fmaxf(v1[e], 0.f); v0[e] = a * a; v1[e] = b * b; } }
;                     if (mode == 1 && colt >= 2048) {
; #pragma unroll
;                         for (int e = 0; e < 4; ++e) { v0[e] = __builtin_amdgcn_rcpf(1.0f + __builtin_amdgcn_exp2f(-1.4426950408889634f * v0[e])); v1[e] = __builtin_amdgcn_rcpf(1.0f + __builtin_amdgcn_exp2f(-1.4426950408889634f * v1[e])); } }
;                     u32x4 w; w.x = cvt_pk_bf16(v0[0], v0[1]); w.y = cvt_pk_bf16(v0[2], v0[3]); w.z = cvt_pk_bf16(v1[0], v1[1]); w.w = cvt_pk_bf16(v1[2], v1[3]);
;                     *(u32x4*)(rowp + bj * HALF) = w; }
.LBB0_392:
	v_cvt_pk_bf16_f32 v90, v90, v91
	v_cvt_pk_bf16_f32 v91, v86, v87
	v_cvt_pk_bf16_f32 v92, v82, v83
	v_cvt_pk_bf16_f32 v93, v88, v89
	s_mov_b32 vcc_lo, 0xff00ff00
	s_mov_b32 vcc_hi, 0xff00ff00
	v_mov_b32_dpp v222, v218 row_ror:8 row_mask:0xf bank_mask:0xf
	v_mov_b32_dpp v223, v219 row_ror:8 row_mask:0xf bank_mask:0xf
	v_mov_b32_dpp v224, v220 row_ror:8 row_mask:0xf bank_mask:0xf
	v_mov_b32_dpp v225, v221 row_ror:8 row_mask:0xf bank_mask:0xf
	v_mov_b32_dpp v242, v90 row_ror:8 row_mask:0xf bank_mask:0xf
	v_mov_b32_dpp v243, v91 row_ror:8 row_mask:0xf bank_mask:0xf
	v_mov_b32_dpp v244, v92 row_ror:8 row_mask:0xf bank_mask:0xf
	v_mov_b32_dpp v245, v93 row_ror:8 row_mask:0xf bank_mask:0xf
	v_lshl_add_u64 v[246:247], v[208:209], 0, v[214:215]
	v_lshl_add_u64 v[248:249], v[208:209], 0, v[216:217]
	v_cndmask_b32_e32 v242, v218, v242, vcc
	v_cndmask_b32_e32 v243, v219, v243, vcc
	v_cndmask_b32_e32 v244, v220, v244, vcc
	v_cndmask_b32_e32 v245, v221, v245, vcc
	v_cndmask_b32_e32 v222, v222, v90, vcc
	v_cndmask_b32_e32 v223, v223, v91, vcc
	v_cndmask_b32_e32 v224, v224, v92, vcc
	v_cndmask_b32_e32 v225, v225, v93, vcc
	global_store_dwordx4 v[246:247], v[242:245], off
	global_store_dwordx4 v[248:249], v[222:225], off
	v_lshl_add_u64 v[208:209], v[208:209], 0, v[212:213]
	s_and_b64 vcc, exec, s[42:43]
	s_nop 1
	v_cvt_f32_u32_e32 v83, v201
	v_cvt_f32_u32_e32 v82, v200
	v_fmamk_f32 v82, v83, 0x4f800000, v82
	v_fmamk_f32 v82, v82, 0x30800000, v229
	v_rsq_f32_e32 v82, v82
	s_nop 0
	v_pk_mul_f32 v[86:87], v[62:63], v[82:83] op_sel_hi:[1,0]
	v_pk_mul_f32 v[90:91], v[60:61], v[82:83] op_sel_hi:[1,0]
	v_pk_mul_f32 v[88:89], v[58:59], v[82:83] op_sel_hi:[1,0]
	v_pk_mul_f32 v[92:93], v[56:57], v[82:83] op_sel_hi:[1,0]
	s_cbranch_vccnz .LBB0_394
	v_max_f32_e32 v84, 0, v90
	v_max_f32_e32 v92, 0, v92
	v_max_f32_e32 v85, 0, v91
	v_max_f32_e32 v93, 0, v93
	v_max_f32_e32 v86, 0, v86
	v_max_f32_e32 v88, 0, v88
	v_max_f32_e32 v87, 0, v87
	v_max_f32_e32 v89, 0, v89
	v_pk_mul_f32 v[90:91], v[84:85], v[84:85]
	v_pk_mul_f32 v[86:87], v[86:87], v[86:87]
	v_pk_mul_f32 v[92:93], v[92:93], v[92:93]
	v_pk_mul_f32 v[88:89], v[88:89], v[88:89]

; __device__ __forceinline__ unsigned cvt_pk_bf16(float lo, float hi) { unsigned r; asm volatile("v_cvt_pk_bf16_f32 %0, %1, %2" : "=v"(r) : "v"(lo), "v"(hi)); return r; }
;     __device__ __forceinline__ void operator()(const f32x4 (&acc)[2][2][4][2], const Unit& u, int wr, int wc, int fr, int fq) const {
;     ...
; #pragma unroll
;         for (int ai = 0; ai < 2; ++ai)
; #pragma unroll
;             for (int m = 0; m < 4; ++m) {
;                 const int r = row0 + ai * HALF + m * 16;
;                 const float rs = __builtin_amdgcn_rsqf((float)ss[r] * (1.0f / 1048576.0f) * (1.0f / 1024.0f) + EPS);
;                 bf16_t* rowp = O + (size_t)r * ldc + colt + wc * 32 + 8 * fq;
; #pragma unroll
;                 for (int bj = 0; bj < 2; ++bj) { f32x4 v0 = acc[ai][bj][m][0] * rs, v1 = acc[ai][bj][m][1] * rs;
;                     if (mode == 2) {
; #pragma unroll
;                         for (int e = 0; e < 4; ++e) { float a = fmaxf(v0[e], 0.f), b = fmaxf(v1[e], 0.f); v0[e] = a * a; v1[e] = b * b; } }
;                     if (mode == 1 && colt >= 2048) {
; #pragma unroll
;                         for (int e = 0; e < 4; ++e) { v0[e] = __builtin_amdgcn_rcpf(1.0f + __builtin_amdgcn_exp2f(-1.4426950408889634f * v0[e])); v1[e] = __builtin_amdgcn_rcpf(1.0f + __builtin_amdgcn_exp2f(-1.4426950408889634f * v1[e])); } }
;                     u32x4 w; w.x = cvt_pk_bf16(v0[0], v0[1]); w.y = cvt_pk_bf16(v0[2], v0[3]); w.z = cvt_pk_bf16(v1[0], v1[1]); w.w = cvt_pk_bf16(v1[2], v1[3]);
;                     *(u32x4*)(rowp + bj * HALF) = w; }
.LBB0_396:
	v_mov_b32_e32 v83, v82
	v_cvt_pk_bf16_f32 v90, v90, v91
	v_cvt_pk_bf16_f32 v91, v86, v87
	v_cvt_pk_bf16_f32 v92, v92, v93
	v_cvt_pk_bf16_f32 v93, v88, v89
	v_mov_b32_e32 v88, v82
	v_mov_b32_e32 v89, v82
	v_mov_b32_e32 v218, v90
	v_mov_b32_e32 v219, v91
	v_mov_b32_e32 v220, v92
	v_mov_b32_e32 v221, v93
	v_pk_mul_f32 v[86:87], v[54:55], v[88:89]
	v_pk_mul_f32 v[88:89], v[50:51], v[88:89]
	v_pk_mul_f32 v[90:91], v[52:53], v[82:83]
	s_and_b64 vcc, exec, s[42:43]
	v_pk_mul_f32 v[82:83], v[48:49], v[82:83]
	s_cbranch_vccnz .LBB0_398
	v_max_f32_e32 v90, 0, v90
	v_max_f32_e32 v82, 0, v82
	v_max_f32_e32 v91, 0, v91
	v_max_f32_e32 v83, 0, v83
	v_max_f32_e32 v86, 0, v86
	v_max_f32_e32 v88, 0, v88
	v_max_f32_e32 v87, 0, v87
	v_max_f32_e32 v89, 0, v89
	v_pk_mul_f32 v[90:91], v[90:91], v[90:91]
	v_pk_mul_f32 v[86:87], v[86:87], v[86:87]
	v_pk_mul_f32 v[82:83], v[82:83], v[82:83]
	v_pk_mul_f32 v[88:89], v[88:89], v[88:89]

; __device__ __forceinline__ unsigned cvt_pk_bf16(float lo, float hi) { unsigned r; asm volatile("v_cvt_pk_bf16_f32 %0, %1, %2" : "=v"(r) : "v"(lo), "v"(hi)); return r; }
;     __device__ __forceinline__ void operator()(const f32x4 (&acc)[2][2][4][2], const Unit& u, int wr, int wc, int fr, int fq) const {
;     ...
; #pragma unroll
;         for (int ai = 0; ai < 2; ++ai)
; #pragma unroll
;             for (int m = 0; m < 4; ++m) {
;                 const int r = row0 + ai * HALF + m * 16;
;                 const float rs = __builtin_amdgcn_rsqf((float)ss[r] * (1.0f / 1048576.0f) * (1.0f / 1024.0f) + EPS);
;                 bf16_t* rowp = O + (size_t)r * ldc + colt + wc * 32 + 8 * fq;
; #pragma unroll
;                 for (int bj = 0; bj < 2; ++bj) { f32x4 v0 = acc[ai][bj][m][0] * rs, v1 = acc[ai][bj][m][1] * rs;
;                     if (mode == 2) {
; #pragma unroll
;                         for (int e = 0; e < 4; ++e) { float a = fmaxf(v0[e], 0.f), b = fmaxf(v1[e], 0.f); v0[e] = a * a; v1[e] = b * b; } }
;                     if (mode == 1 && colt >= 2048) {
; #pragma unroll
;                         for (int e = 0; e < 4; ++e) { v0[e] = __builtin_amdgcn_rcpf(1.0f + __builtin_amdgcn_exp2f(-1.4426950408889634f * v0[e])); v1[e] = __builtin_amdgcn_rcpf(1.0f + __builtin_amdgcn_exp2f(-1.4426950408889634f * v1[e])); } }
;                     u32x4 w; w.x = cvt_pk_bf16(v0[0], v0[1]); w.y = cvt_pk_bf16(v0[2], v0[3]); w.z = cvt_pk_bf16(v1[0], v1[1]); w.w = cvt_pk_bf16(v1[2], v1[3]);
;                     *(u32x4*)(rowp + bj * HALF) = w; }
.LBB0_400:
	v_cvt_pk_bf16_f32 v90, v90, v91
	v_cvt_pk_bf16_f32 v91, v86, v87
	v_cvt_pk_bf16_f32 v92, v82, v83
	v_cvt_pk_bf16_f32 v93, v88, v89
	s_mov_b32 vcc_lo, 0xff00ff00
	s_mov_b32 vcc_hi, 0xff00ff00
	v_mov_b32_dpp v222, v218 row_ror:8 row_mask:0xf bank_mask:0xf
	v_mov_b32_dpp v223, v219 row_ror:8 row_mask:0xf bank_mask:0xf
	v_mov_b32_dpp v224, v220 row_ror:8 row_mask:0xf bank_mask:0xf
	v_mov_b32_dpp v225, v221 row_ror:8 row_mask:0xf bank_mask:0xf
	v_mov_b32_dpp v242, v90 row_ror:8 row_mask:0xf bank_mask:0xf
	v_mov_b32_dpp v243, v91 row_ror:8 row_mask:0xf bank_mask:0xf
	v_mov_b32_dpp v244, v92 row_ror:8 row_mask:0xf bank_mask:0xf
	v_mov_b32_dpp v245, v93 row_ror:8 row_mask:0xf bank_mask:0xf
	v_lshl_add_u64 v[246:247], v[208:209], 0, v[214:215]
	v_lshl_add_u64 v[248:249], v[208:209], 0, v[216:217]
	v_cndmask_b32_e32 v242, v218, v242, vcc
	v_cndmask_b32_e32 v243, v219, v243, vcc
	v_cndmask_b32_e32 v244, v220, v244, vcc
	v_cndmask_b32_e32 v245, v221, v245, vcc
	v_cndmask_b32_e32 v222, v222, v90, vcc
	v_cndmask_b32_e32 v223, v223, v91, vcc
	v_cndmask_b32_e32 v224, v224, v92, vcc
	v_cndmask_b32_e32 v225, v225, v93, vcc
	global_store_dwordx4 v[246:247], v[242:245], off
	global_store_dwordx4 v[248:249], v[222:225], off
	v_lshl_add_u64 v[208:209], v[208:209], 0, v[210:211]
	s_and_b64 vcc, exec, s[42:43]
	s_nop 1
	v_cvt_f32_u32_e32 v83, v203
	v_cvt_f32_u32_e32 v82, v202
	v_fmamk_f32 v82, v83, 0x4f800000, v82
	v_fmamk_f32 v82, v82, 0x30800000, v229
	v_rsq_f32_e32 v82, v82
	s_nop 0
	v_pk_mul_f32 v[86:87], v[46:47], v[82:83] op_sel_hi:[1,0]
	v_pk_mul_f32 v[90:91], v[44:45], v[82:83] op_sel_hi:[1,0]
	v_pk_mul_f32 v[88:89], v[42:43], v[82:83] op_sel_hi:[1,0]
	v_pk_mul_f32 v[92:93], v[40:41], v[82:83] op_sel_hi:[1,0]
	s_cbranch_vccnz .LBB0_402
	v_max_f32_e32 v84, 0, v90
	v_max_f32_e32 v92, 0, v92
	v_max_f32_e32 v85, 0, v91
	v_max_f32_e32 v93, 0, v93
	v_max_f32_e32 v86, 0, v86
	v_max_f32_e32 v88, 0, v88
	v_max_f32_e32 v87, 0, v87
	v_max_f32_e32 v89, 0, v89
	v_pk_mul_f32 v[90:91], v[84:85], v[84:85]
	v_pk_mul_f32 v[86:87], v[86:87], v[86:87]
	v_pk_mul_f32 v[92:93], v[92:93], v[92:93]
	v_pk_mul_f32 v[88:89], v[88:89], v[88:89]

; __device__ __forceinline__ unsigned cvt_pk_bf16(float lo, float hi) { unsigned r; asm volatile("v_cvt_pk_bf16_f32 %0, %1, %2" : "=v"(r) : "v"(lo), "v"(hi)); return r; }
;     __device__ __forceinline__ void operator()(const f32x4 (&acc)[2][2][4][2], const Unit& u, int wr, int wc, int fr, int fq) const {
;     ...
; #pragma unroll
;         for (int ai = 0; ai < 2; ++ai)
; #pragma unroll
;             for (int m = 0; m < 4; ++m) {
;                 const int r = row0 + ai * HALF + m * 16;
;                 const float rs = __builtin_amdgcn_rsqf((float)ss[r] * (1.0f / 1048576.0f) * (1.0f / 1024.0f) + EPS);
;                 bf16_t* rowp = O + (size_t)r * ldc + colt + wc * 32 + 8 * fq;
; #pragma unroll
;                 for (int bj = 0; bj < 2; ++bj) { f32x4 v0 = acc[ai][bj][m][0] * rs, v1 = acc[ai][bj][m][1] * rs;
;                     if (mode == 2) {
; #pragma unroll
;                         for (int e = 0; e < 4; ++e) { float a = fmaxf(v0[e], 0.f), b = fmaxf(v1[e], 0.f); v0[e] = a * a; v1[e] = b * b; } }
;                     if (mode == 1 && colt >= 2048) {
; #pragma unroll
;                         for (int e = 0; e < 4; ++e) { v0[e] = __builtin_amdgcn_rcpf(1.0f + __builtin_amdgcn_exp2f(-1.4426950408889634f * v0[e])); v1[e] = __builtin_amdgcn_rcpf(1.0f + __builtin_amdgcn_exp2f(-1.4426950408889634f * v1[e])); } }
;                     u32x4 w; w.x = cvt_pk_bf16(v0[0], v0[1]); w.y = cvt_pk_bf16(v0[2], v0[3]); w.z = cvt_pk_bf16(v1[0], v1[1]); w.w = cvt_pk_bf16(v1[2], v1[3]);
;                     *(u32x4*)(rowp + bj * HALF) = w; }
.LBB0_404:
	v_mov_b32_e32 v83, v82
	v_cvt_pk_bf16_f32 v90, v90, v91
	v_cvt_pk_bf16_f32 v91, v86, v87
	v_cvt_pk_bf16_f32 v92, v92, v93
	v_cvt_pk_bf16_f32 v93, v88, v89
	v_mov_b32_e32 v88, v82
	v_mov_b32_e32 v89, v82
	v_mov_b32_e32 v218, v90
	v_mov_b32_e32 v219, v91
	v_mov_b32_e32 v220, v92
	v_mov_b32_e32 v221, v93
	v_pk_mul_f32 v[86:87], v[38:39], v[88:89]
	v_pk_mul_f32 v[88:89], v[34:35], v[88:89]
	v_pk_mul_f32 v[90:91], v[36:37], v[82:83]
	s_and_b64 vcc, exec, s[42:43]
	v_pk_mul_f32 v[82:83], v[32:33], v[82:83]
	s_cbranch_vccnz .LBB0_406
	v_max_f32_e32 v90, 0, v90
	v_max_f32_e32 v82, 0, v82
	v_max_f32_e32 v91, 0, v91
	v_max_f32_e32 v83, 0, v83
	v_max_f32_e32 v86, 0, v86
	v_max_f32_e32 v88, 0, v88
	v_max_f32_e32 v87, 0, v87
	v_max_f32_e32 v89, 0, v89
	v_pk_mul_f32 v[90:91], v[90:91], v[90:91]
	v_pk_mul_f32 v[86:87], v[86:87], v[86:87]
	v_pk_mul_f32 v[82:83], v[82:83], v[82:83]
	v_pk_mul_f32 v[88:89], v[88:89], v[88:89]

; __device__ __forceinline__ unsigned cvt_pk_bf16(float lo, float hi) { unsigned r; asm volatile("v_cvt_pk_bf16_f32 %0, %1, %2" : "=v"(r) : "v"(lo), "v"(hi)); return r; }
;     __device__ __forceinline__ void operator()(const f32x4 (&acc)[2][2][4][2], const Unit& u, int wr, int wc, int fr, int fq) const {
;     ...
; #pragma unroll
;         for (int ai = 0; ai < 2; ++ai)
; #pragma unroll
;             for (int m = 0; m < 4; ++m) {
;                 const int r = row0 + ai * HALF + m * 16;
;                 const float rs = __builtin_amdgcn_rsqf((float)ss[r] * (1.0f / 1048576.0f) * (1.0f / 1024.0f) + EPS);
;                 bf16_t* rowp = O + (size_t)r * ldc + colt + wc * 32 + 8 * fq;
; #pragma unroll
;                 for (int bj = 0; bj < 2; ++bj) { f32x4 v0 = acc[ai][bj][m][0] * rs, v1 = acc[ai][bj][m][1] * rs;
;                     if (mode == 2) {
; #pragma unroll
;                         for (int e = 0; e < 4; ++e) { float a = fmaxf(v0[e], 0.f), b = fmaxf(v1[e], 0.f); v0[e] = a * a; v1[e] = b * b; } }
;                     if (mode == 1 && colt >= 2048) {
; #pragma unroll
;                         for (int e = 0; e < 4; ++e) { v0[e] = __builtin_amdgcn_rcpf(1.0f + __builtin_amdgcn_exp2f(-1.4426950408889634f * v0[e])); v1[e] = __builtin_amdgcn_rcpf(1.0f + __builtin_amdgcn_exp2f(-1.4426950408889634f * v1[e])); } }
;                     u32x4 w; w.x = cvt_pk_bf16(v0[0], v0[1]); w.y = cvt_pk_bf16(v0[2], v0[3]); w.z = cvt_pk_bf16(v1[0], v1[1]); w.w = cvt_pk_bf16(v1[2], v1[3]);
;                     *(u32x4*)(rowp + bj * HALF) = w; }
.LBB0_408:
	v_cvt_pk_bf16_f32 v90, v90, v91
	v_cvt_pk_bf16_f32 v91, v86, v87
	v_cvt_pk_bf16_f32 v92, v82, v83
	v_cvt_pk_bf16_f32 v93, v88, v89
	s_mov_b32 vcc_lo, 0xff00ff00
	s_mov_b32 vcc_hi, 0xff00ff00
	v_mov_b32_dpp v222, v218 row_ror:8 row_mask:0xf bank_mask:0xf
	v_mov_b32_dpp v223, v219 row_ror:8 row_mask:0xf bank_mask:0xf
	v_mov_b32_dpp v224, v220 row_ror:8 row_mask:0xf bank_mask:0xf
	v_mov_b32_dpp v225, v221 row_ror:8 row_mask:0xf bank_mask:0xf
	v_mov_b32_dpp v242, v90 row_ror:8 row_mask:0xf bank_mask:0xf
	v_mov_b32_dpp v243, v91 row_ror:8 row_mask:0xf bank_mask:0xf
	v_mov_b32_dpp v244, v92 row_ror:8 row_mask:0xf bank_mask:0xf
	v_mov_b32_dpp v245, v93 row_ror:8 row_mask:0xf bank_mask:0xf
	v_lshl_add_u64 v[246:247], v[208:209], 0, v[214:215]
	v_lshl_add_u64 v[248:249], v[208:209], 0, v[216:217]
	v_cndmask_b32_e32 v242, v218, v242, vcc
	v_cndmask_b32_e32 v243, v219, v243, vcc
	v_cndmask_b32_e32 v244, v220, v244, vcc
	v_cndmask_b32_e32 v245, v221, v245, vcc
	v_cndmask_b32_e32 v222, v222, v90, vcc
	v_cndmask_b32_e32 v223, v223, v91, vcc
	v_cndmask_b32_e32 v224, v224, v92, vcc
	v_cndmask_b32_e32 v225, v225, v93, vcc
	global_store_dwordx4 v[246:247], v[242:245], off
	global_store_dwordx4 v[248:249], v[222:225], off
	v_lshl_add_u64 v[208:209], v[208:209], 0, v[210:211]
	s_and_b64 vcc, exec, s[42:43]
	s_nop 1
	v_cvt_f32_u32_e32 v83, v205
	v_cvt_f32_u32_e32 v82, v204
	v_fmamk_f32 v82, v83, 0x4f800000, v82
	v_fmamk_f32 v82, v82, 0x30800000, v229
	v_rsq_f32_e32 v82, v82
	s_nop 0
	v_pk_mul_f32 v[86:87], v[30:31], v[82:83] op_sel_hi:[1,0]
	v_pk_mul_f32 v[90:91], v[28:29], v[82:83] op_sel_hi:[1,0]
	v_pk_mul_f32 v[88:89], v[26:27], v[82:83] op_sel_hi:[1,0]
	v_pk_mul_f32 v[92:93], v[24:25], v[82:83] op_sel_hi:[1,0]
	s_cbranch_vccnz .LBB0_410
	v_max_f32_e32 v84, 0, v90
	v_max_f32_e32 v92, 0, v92
	v_max_f32_e32 v85, 0, v91
	v_max_f32_e32 v93, 0, v93
	v_max_f32_e32 v86, 0, v86
	v_max_f32_e32 v88, 0, v88
	v_max_f32_e32 v87, 0, v87
	v_max_f32_e32 v89, 0, v89
	v_pk_mul_f32 v[90:91], v[84:85], v[84:85]
	v_pk_mul_f32 v[86:87], v[86:87], v[86:87]
	v_pk_mul_f32 v[92:93], v[92:93], v[92:93]
	v_pk_mul_f32 v[88:89], v[88:89], v[88:89]

; __device__ __forceinline__ unsigned cvt_pk_bf16(float lo, float hi) { unsigned r; asm volatile("v_cvt_pk_bf16_f32 %0, %1, %2" : "=v"(r) : "v"(lo), "v"(hi)); return r; }
;     __device__ __forceinline__ void operator()(const f32x4 (&acc)[2][2][4][2], const Unit& u, int wr, int wc, int fr, int fq) const {
;     ...
; #pragma unroll
;         for (int ai = 0; ai < 2; ++ai)
; #pragma unroll
;             for (int m = 0; m < 4; ++m) {
;                 const int r = row0 + ai * HALF + m * 16;
;                 const float rs = __builtin_amdgcn_rsqf((float)ss[r] * (1.0f / 1048576.0f) * (1.0f / 1024.0f) + EPS);
;                 bf16_t* rowp = O + (size_t)r * ldc + colt + wc * 32 + 8 * fq;
; #pragma unroll
;                 for (int bj = 0; bj < 2; ++bj) { f32x4 v0 = acc[ai][bj][m][0] * rs, v1 = acc[ai][bj][m][1] * rs;
;                     if (mode == 2) {
; #pragma unroll
;                         for (int e = 0; e < 4; ++e) { float a = fmaxf(v0[e], 0.f), b = fmaxf(v1[e], 0.f); v0[e] = a * a; v1[e] = b * b; } }
;                     if (mode == 1 && colt >= 2048) {
; #pragma unroll
;                         for (int e = 0; e < 4; ++e) { v0[e] = __builtin_amdgcn_rcpf(1.0f + __builtin_amdgcn_exp2f(-1.4426950408889634f * v0[e])); v1[e] = __builtin_amdgcn_rcpf(1.0f + __builtin_amdgcn_exp2f(-1.4426950408889634f * v1[e])); } }
;                     u32x4 w; w.x = cvt_pk_bf16(v0[0], v0[1]); w.y = cvt_pk_bf16(v0[2], v0[3]); w.z = cvt_pk_bf16(v1[0], v1[1]); w.w = cvt_pk_bf16(v1[2], v1[3]);
;                     *(u32x4*)(rowp + bj * HALF) = w; }
.LBB0_412:
	v_mov_b32_e32 v83, v82
	v_cvt_pk_bf16_f32 v90, v90, v91
	v_cvt_pk_bf16_f32 v91, v86, v87
	v_cvt_pk_bf16_f32 v92, v92, v93
	v_cvt_pk_bf16_f32 v93, v88, v89
	v_mov_b32_e32 v88, v82
	v_mov_b32_e32 v89, v82
	v_mov_b32_e32 v218, v90
	v_mov_b32_e32 v219, v91
	v_mov_b32_e32 v220, v92
	v_mov_b32_e32 v221, v93
	v_pk_mul_f32 v[86:87], v[22:23], v[88:89]
	v_pk_mul_f32 v[88:89], v[18:19], v[88:89]
	v_pk_mul_f32 v[90:91], v[20:21], v[82:83]
	s_and_b64 vcc, exec, s[42:43]
	v_pk_mul_f32 v[82:83], v[16:17], v[82:83]
	s_cbranch_vccnz .LBB0_414
	v_max_f32_e32 v90, 0, v90
	v_max_f32_e32 v82, 0, v82
	v_max_f32_e32 v91, 0, v91
	v_max_f32_e32 v83, 0, v83
	v_max_f32_e32 v86, 0, v86
	v_max_f32_e32 v88, 0, v88
	v_max_f32_e32 v87, 0, v87
	v_max_f32_e32 v89, 0, v89
	v_pk_mul_f32 v[90:91], v[90:91], v[90:91]
	v_pk_mul_f32 v[86:87], v[86:87], v[86:87]
	v_pk_mul_f32 v[82:83], v[82:83], v[82:83]
	v_pk_mul_f32 v[88:89], v[88:89], v[88:89]

; __device__ __forceinline__ unsigned cvt_pk_bf16(float lo, float hi) { unsigned r; asm volatile("v_cvt_pk_bf16_f32 %0, %1, %2" : "=v"(r) : "v"(lo), "v"(hi)); return r; }
;     __device__ __forceinline__ void operator()(const f32x4 (&acc)[2][2][4][2], const Unit& u, int wr, int wc, int fr, int fq) const {
;     ...
; #pragma unroll
;         for (int ai = 0; ai < 2; ++ai)
; #pragma unroll
;             for (int m = 0; m < 4; ++m) {
;                 const int r = row0 + ai * HALF + m * 16;
;                 const float rs = __builtin_amdgcn_rsqf((float)ss[r] * (1.0f / 1048576.0f) * (1.0f / 1024.0f) + EPS);
;                 bf16_t* rowp = O + (size_t)r * ldc + colt + wc * 32 + 8 * fq;
; #pragma unroll
;                 for (int bj = 0; bj < 2; ++bj) { f32x4 v0 = acc[ai][bj][m][0] * rs, v1 = acc[ai][bj][m][1] * rs;
;                     if (mode == 2) {
; #pragma unroll
;                         for (int e = 0; e < 4; ++e) { float a = fmaxf(v0[e], 0.f), b = fmaxf(v1[e], 0.f); v0[e] = a * a; v1[e] = b * b; } }
;                     if (mode == 1 && colt >= 2048) {
; #pragma unroll
;                         for (int e = 0; e < 4; ++e) { v0[e] = __builtin_amdgcn_rcpf(1.0f + __builtin_amdgcn_exp2f(-1.4426950408889634f * v0[e])); v1[e] = __builtin_amdgcn_rcpf(1.0f + __builtin_amdgcn_exp2f(-1.4426950408889634f * v1[e])); } }
;                     u32x4 w; w.x = cvt_pk_bf16(v0[0], v0[1]); w.y = cvt_pk_bf16(v0[2], v0[3]); w.z = cvt_pk_bf16(v1[0], v1[1]); w.w = cvt_pk_bf16(v1[2], v1[3]);
;                     *(u32x4*)(rowp + bj * HALF) = w; }
.LBB0_416:
	v_cvt_pk_bf16_f32 v90, v90, v91
	v_cvt_pk_bf16_f32 v91, v86, v87
	v_cvt_pk_bf16_f32 v92, v82, v83
	v_cvt_pk_bf16_f32 v93, v88, v89
	s_mov_b32 vcc_lo, 0xff00ff00
	s_mov_b32 vcc_hi, 0xff00ff00
	v_mov_b32_dpp v222, v218 row_ror:8 row_mask:0xf bank_mask:0xf
	v_mov_b32_dpp v223, v219 row_ror:8 row_mask:0xf bank_mask:0xf
	v_mov_b32_dpp v224, v220 row_ror:8 row_mask:0xf bank_mask:0xf
	v_mov_b32_dpp v225, v221 row_ror:8 row_mask:0xf bank_mask:0xf
	v_mov_b32_dpp v242, v90 row_ror:8 row_mask:0xf bank_mask:0xf
	v_mov_b32_dpp v243, v91 row_ror:8 row_mask:0xf bank_mask:0xf
	v_mov_b32_dpp v244, v92 row_ror:8 row_mask:0xf bank_mask:0xf
	v_mov_b32_dpp v245, v93 row_ror:8 row_mask:0xf bank_mask:0xf
	v_lshl_add_u64 v[246:247], v[208:209], 0, v[214:215]
	v_lshl_add_u64 v[248:249], v[208:209], 0, v[216:217]
	v_cndmask_b32_e32 v242, v218, v242, vcc
	v_cndmask_b32_e32 v243, v219, v243, vcc
	v_cndmask_b32_e32 v244, v220, v244, vcc
	v_cndmask_b32_e32 v245, v221, v245, vcc
	v_cndmask_b32_e32 v222, v222, v90, vcc
	v_cndmask_b32_e32 v223, v223, v91, vcc
	v_cndmask_b32_e32 v224, v224, v92, vcc
	v_cndmask_b32_e32 v225, v225, v93, vcc
	global_store_dwordx4 v[246:247], v[242:245], off
	global_store_dwordx4 v[248:249], v[222:225], off
	v_lshl_add_u64 v[208:209], v[208:209], 0, v[210:211]
	s_and_b64 vcc, exec, s[42:43]
	s_nop 1
	v_cvt_f32_u32_e32 v81, v207
	v_cvt_f32_u32_e32 v80, v206
	v_fmamk_f32 v80, v81, 0x4f800000, v80
	v_fmamk_f32 v80, v80, 0x30800000, v229
	v_rsq_f32_e32 v80, v80
	s_nop 0
	v_pk_mul_f32 v[84:85], v[14:15], v[80:81] op_sel_hi:[1,0]
	v_pk_mul_f32 v[88:89], v[12:13], v[80:81] op_sel_hi:[1,0]
	v_pk_mul_f32 v[86:87], v[10:11], v[80:81] op_sel_hi:[1,0]
	v_pk_mul_f32 v[90:91], v[8:9], v[80:81] op_sel_hi:[1,0]
	s_cbranch_vccnz .LBB0_418
	v_max_f32_e32 v82, 0, v88
	v_max_f32_e32 v90, 0, v90
	v_max_f32_e32 v83, 0, v89
	v_max_f32_e32 v91, 0, v91
	v_max_f32_e32 v84, 0, v84
	v_max_f32_e32 v86, 0, v86
	v_max_f32_e32 v85, 0, v85
	v_max_f32_e32 v87, 0, v87
	v_pk_mul_f32 v[88:89], v[82:83], v[82:83]
	v_pk_mul_f32 v[84:85], v[84:85], v[84:85]
	v_pk_mul_f32 v[90:91], v[90:91], v[90:91]
	v_pk_mul_f32 v[86:87], v[86:87], v[86:87]

; __device__ __forceinline__ unsigned cvt_pk_bf16(float lo, float hi) { unsigned r; asm volatile("v_cvt_pk_bf16_f32 %0, %1, %2" : "=v"(r) : "v"(lo), "v"(hi)); return r; }
;     __device__ __forceinline__ void operator()(const f32x4 (&acc)[2][2][4][2], const Unit& u, int wr, int wc, int fr, int fq) const {
;     ...
; #pragma unroll
;         for (int ai = 0; ai < 2; ++ai)
; #pragma unroll
;             for (int m = 0; m < 4; ++m) {
;                 const int r = row0 + ai * HALF + m * 16;
;                 const float rs = __builtin_amdgcn_rsqf((float)ss[r] * (1.0f / 1048576.0f) * (1.0f / 1024.0f) + EPS);
;                 bf16_t* rowp = O + (size_t)r * ldc + colt + wc * 32 + 8 * fq;
; #pragma unroll
;                 for (int bj = 0; bj < 2; ++bj) { f32x4 v0 = acc[ai][bj][m][0] * rs, v1 = acc[ai][bj][m][1] * rs;
;                     if (mode == 2) {
; #pragma unroll
;                         for (int e = 0; e < 4; ++e) { float a = fmaxf(v0[e], 0.f), b = fmaxf(v1[e], 0.f); v0[e] = a * a; v1[e] = b * b; } }
;                     if (mode == 1 && colt >= 2048) {
; #pragma unroll
;                         for (int e = 0; e < 4; ++e) { v0[e] = __builtin_amdgcn_rcpf(1.0f + __builtin_amdgcn_exp2f(-1.4426950408889634f * v0[e])); v1[e] = __builtin_amdgcn_rcpf(1.0f + __builtin_amdgcn_exp2f(-1.4426950408889634f * v1[e])); } }
;                     u32x4 w; w.x = cvt_pk_bf16(v0[0], v0[1]); w.y = cvt_pk_bf16(v0[2], v0[3]); w.z = cvt_pk_bf16(v1[0], v1[1]); w.w = cvt_pk_bf16(v1[2], v1[3]);
;                     *(u32x4*)(rowp + bj * HALF) = w; }
.LBB0_420:
	v_mov_b32_e32 v81, v80
	v_cvt_pk_bf16_f32 v88, v88, v89
	v_cvt_pk_bf16_f32 v89, v84, v85
	v_mov_b32_e32 v84, v80
	v_mov_b32_e32 v85, v80
	v_cvt_pk_bf16_f32 v90, v90, v91
	v_cvt_pk_bf16_f32 v91, v86, v87
	v_mov_b32_e32 v218, v88
	v_mov_b32_e32 v219, v89
	v_mov_b32_e32 v220, v90
	v_mov_b32_e32 v221, v91
	v_pk_mul_f32 v[86:87], v[6:7], v[84:85]
	v_pk_mul_f32 v[84:85], v[2:3], v[84:85]
	v_pk_mul_f32 v[88:89], v[4:5], v[80:81]
	s_and_b64 vcc, exec, s[42:43]
	v_pk_mul_f32 v[80:81], v[0:1], v[80:81]
	s_cbranch_vccnz .LBB0_422
	v_max_f32_e32 v88, 0, v88
	v_max_f32_e32 v80, 0, v80
	v_max_f32_e32 v89, 0, v89
	v_max_f32_e32 v81, 0, v81
	v_max_f32_e32 v86, 0, v86
	v_max_f32_e32 v84, 0, v84
	v_max_f32_e32 v87, 0, v87
	v_max_f32_e32 v85, 0, v85
	v_pk_mul_f32 v[88:89], v[88:89], v[88:89]
	v_pk_mul_f32 v[86:87], v[86:87], v[86:87]
	v_pk_mul_f32 v[80:81], v[80:81], v[80:81]
	v_pk_mul_f32 v[84:85], v[84:85], v[84:85]

; __device__ __forceinline__ unsigned cvt_pk_bf16(float lo, float hi) { unsigned r; asm volatile("v_cvt_pk_bf16_f32 %0, %1, %2" : "=v"(r) : "v"(lo), "v"(hi)); return r; }
;     __device__ __forceinline__ void operator()(const f32x4 (&acc)[2][2][4][2], const Unit& u, int wr, int wc, int fr, int fq) const {
;     ...
; #pragma unroll
;         for (int ai = 0; ai < 2; ++ai)
; #pragma unroll
;             for (int m = 0; m < 4; ++m) {
;                 const int r = row0 + ai * HALF + m * 16;
;                 const float rs = __builtin_amdgcn_rsqf((float)ss[r] * (1.0f / 1048576.0f) * (1.0f / 1024.0f) + EPS);
;                 bf16_t* rowp = O + (size_t)r * ldc + colt + wc * 32 + 8 * fq;
; #pragma unroll
;                 for (int bj = 0; bj < 2; ++bj) { f32x4 v0 = acc[ai][bj][m][0] * rs, v1 = acc[ai][bj][m][1] * rs;
;                     if (mode == 2) {
; #pragma unroll
;                         for (int e = 0; e < 4; ++e) { float a = fmaxf(v0[e], 0.f), b = fmaxf(v1[e], 0.f); v0[e] = a * a; v1[e] = b * b; } }
;                     if (mode == 1 && colt >= 2048) {
; #pragma unroll
;                         for (int e = 0; e < 4; ++e) { v0[e] = __builtin_amdgcn_rcpf(1.0f + __builtin_amdgcn_exp2f(-1.4426950408889634f * v0[e])); v1[e] = __builtin_amdgcn_rcpf(1.0f + __builtin_amdgcn_exp2f(-1.4426950408889634f * v1[e])); } }
;                     u32x4 w; w.x = cvt_pk_bf16(v0[0], v0[1]); w.y = cvt_pk_bf16(v0[2], v0[3]); w.z = cvt_pk_bf16(v1[0], v1[1]); w.w = cvt_pk_bf16(v1[2], v1[3]);
;                     *(u32x4*)(rowp + bj * HALF) = w; }
.LBB0_424:
	v_cvt_pk_bf16_f32 v88, v88, v89
	v_cvt_pk_bf16_f32 v89, v86, v87
	v_cvt_pk_bf16_f32 v90, v80, v81
	v_cvt_pk_bf16_f32 v91, v84, v85
	s_mov_b32 vcc_lo, 0xff00ff00
	s_mov_b32 vcc_hi, 0xff00ff00
	v_mov_b32_dpp v222, v218 row_ror:8 row_mask:0xf bank_mask:0xf
	v_mov_b32_dpp v223, v219 row_ror:8 row_mask:0xf bank_mask:0xf
	v_mov_b32_dpp v224, v220 row_ror:8 row_mask:0xf bank_mask:0xf
	v_mov_b32_dpp v225, v221 row_ror:8 row_mask:0xf bank_mask:0xf
	v_mov_b32_dpp v242, v88 row_ror:8 row_mask:0xf bank_mask:0xf
	v_mov_b32_dpp v243, v89 row_ror:8 row_mask:0xf bank_mask:0xf
	v_mov_b32_dpp v244, v90 row_ror:8 row_mask:0xf bank_mask:0xf
	v_mov_b32_dpp v245, v91 row_ror:8 row_mask:0xf bank_mask:0xf
	v_lshl_add_u64 v[246:247], v[208:209], 0, v[214:215]
	v_lshl_add_u64 v[248:249], v[208:209], 0, v[216:217]
	v_cndmask_b32_e32 v242, v218, v242, vcc
	v_cndmask_b32_e32 v243, v219, v243, vcc
	v_cndmask_b32_e32 v244, v220, v244, vcc
	v_cndmask_b32_e32 v245, v221, v245, vcc
	v_cndmask_b32_e32 v222, v222, v88, vcc
	v_cndmask_b32_e32 v223, v223, v89, vcc
	v_cndmask_b32_e32 v224, v224, v90, vcc
	v_cndmask_b32_e32 v225, v225, v91, vcc
	global_store_dwordx4 v[246:247], v[242:245], off
	global_store_dwordx4 v[248:249], v[222:225], off
	s_branch .LBB0_359

; DI void prologue(const Args& a, LAS unsigned char* lds, int G, int bid) {
;     ...
;         if (mi < 2)       { W = a.in[4] + (size_t)mi * 1024 * 9216; ldw = 9216; K = 1024; N = 9216; g = a.in[1] + (2 * mi) * 1024; WT = (bf16_t*)(ws + W_AIN + (size_t)mi * 18 * MiB); }
;         else if (mi < 4)  { const int j = mi - 2; W = a.in[7] + (size_t)j * 1024 * 1024; ldw = 1024; K = 1024; N = 1024; g = nullptr; WT = (bf16_t*)(ws + W_AOUT + (size_t)j * 2 * MiB); }
;         else if (mi < 6)  { const int j = mi - 4; W = a.in[8] + (size_t)j * 1024 * 3080; ldw = 3080; K = 1024; N = 3072; g = a.in[1] + (2 * j + 1) * 1024; WT = (bf16_t*)(ws + W_MIN + (size_t)j * 6 * MiB); }
;         else if (mi < 8)  { const int j = mi - 6; W = a.in[13] + (size_t)j * 1024 * 1024; ldw = 1024; K = 1024; N = 1024; g = nullptr; WT = (bf16_t*)(ws + W_MOUT + (size_t)j * 2 * MiB); }
;         else if (mi < 12) { const int l = mi - 8; W = a.in[14] + (size_t)l * 1024 * 4096; ldw = 4096; K = 1024; N = 4096; g = a.in[2] + l * 1024; WT = (bf16_t*)(ws + W_UP + (size_t)l * 8 * MiB); }
;         else              { const int l = mi - 12; W = a.in[15] + (size_t)l * 4096 * 1024; ldw = 1024; K = 4096; N = 1024; g = nullptr; WT = (bf16_t*)(ws + W_DN + (size_t)l * 8 * MiB); }
;         const int nblk = N / 64, nit = (K / 64) * nblk;
;         int first = (gw - (base % NGW) + NGW) % NGW;
;         for (int it = first; it < nit; it += NGW) transpose_item(W, ldw, K, nblk, g, WT, scr, it, lane, mi < 2);
.LBB0_459:
	s_bitcmp1_b32 0xf33, s51
	s_cselect_b64 s[38:39], -1, 0
	s_cmp_gt_u32 s51, 1
	s_mov_b64 s[42:43], -1
	s_cbranch_scc0 .LBB0_476
	s_cmp_gt_u32 s51, 3
	s_cbranch_scc0 .LBB0_473
	s_cmp_gt_u32 s51, 5
	s_cbranch_scc0 .LBB0_470
	s_cmp_gt_u32 s51, 7
	s_cbranch_scc0 .LBB0_467
	s_cmp_gt_u32 s51, 11
	s_mov_b64 s[0:1], -1
	s_cbranch_scc0 .LBB0_465
	s_add_i32 s34, s51, -12
	v_readlane_b32 s60, v251, 39
	s_lshl_b64 s[0:1], s[34:35], 24
	v_readlane_b32 s74, v251, 53
	v_readlane_b32 s75, v251, 54
	s_add_u32 s44, s74, s0
	s_addc_u32 s45, s75, s1
	s_lshl_b64 s[0:1], s[34:35], 23
	v_readlane_b32 s2, v251, 11
	s_add_u32 s48, s2, s0
	v_readlane_b32 s0, v251, 12
	v_readlane_b32 s61, v251, 40
	v_readlane_b32 s62, v251, 41
	v_readlane_b32 s63, v251, 42
	v_readlane_b32 s64, v251, 43
	v_readlane_b32 s65, v251, 44
	v_readlane_b32 s66, v251, 45
	v_readlane_b32 s67, v251, 46
	v_readlane_b32 s68, v251, 47
	v_readlane_b32 s69, v251, 48
	v_readlane_b32 s70, v251, 49
	v_readlane_b32 s71, v251, 50
	v_readlane_b32 s72, v251, 51
	v_readlane_b32 s73, v251, 52
	s_addc_u32 s49, s0, s1
	s_mov_b64 s[0:1], 0
